# hand-written scan compute loop v3 (row-pair packed state, operands reloaded in place two steps ahead, 625 vs 758 instr per chunk), compute prio 1
# speedup vs baseline: 1.0105x; 1.0105x over previous
; __device__ __forceinline__ void scan_item(LAS unsigned char* lds, const ScanPtrs& P, bf16* YC, int item, unsigned* half_cnt, unsigned half_expect) {
;     ...
;         const int g = lane & 15, ra = 8 * wid + (lane >> 4);
;         f32x2 A01 = {0.f, 0.f}, A23 = {0.f, 0.f}, B01 = {0.f, 0.f}, B23 = {0.f, 0.f};
;         __builtin_amdgcn_s_setprio(3);
;         __syncthreads();
;         for (int c = 0; c < NCH; ++c) {
;             const LAS float* Bk = inb + (c & 1) * SC_INB + 4 * g;
;             const LAS float* Bv = inb + (c & 1) * SC_INB + 320 + ra;
;             LAS float* Y = ypb + (c & 1) * SC_YB + ra * 16 + g;
;             f32x4 cw, cm, cwr, ck, cr, nw, nm, nwr, nk, nr; float cva, cvb, nva, nvb;
;     ...
;             SC_RD(0, cw, cm, cwr, ck, cr, cva, cvb);
; #pragma unroll
;             for (int s = 0; s < SC_TC; ++s) {
;                 if (s + 1 < SC_TC) SC_RD(s + 1, nw, nm, nwr, nk, nr, nva, nvb);
;                 __builtin_amdgcn_sched_barrier(0);
;                 const f32x2 m01 = {cm[0], cm[1]}, m23 = {cm[2], cm[3]}, w01 = {cw[0], cw[1]}, w23 = {cw[2], cw[3]}, wr01 = {cwr[0], cwr[1]}, wr23 = {cwr[2], cwr[3]},
;                             k01 = {ck[0], ck[1]}, k23 = {ck[2], ck[3]}, r01 = {cr[0], cr[1]}, r23 = {cr[2], cr[3]};
;                 f32x2 qa = A01 * m01; qa = __builtin_elementwise_fma(A23, m23, qa);
;                 f32x2 qb = B01 * m01; qb = __builtin_elementwise_fma(B23, m23, qb);
;                 float da = qa[0] + qa[1], db = qb[0] + qb[1];
;                 const f32x2 vka01 = k01 * cva, vka23 = k23 * cva, vkb01 = k01 * cvb, vkb23 = k23 * cvb;
;                 da += dppf<0xB1>(da);  db += dppf<0xB1>(db);
;                 da += dppf<0x4E>(da);  db += dppf<0x4E>(db);
;                 da += dppf<0x141>(da); db += dppf<0x141>(db);
;                 da += dppf<0x140>(da); db += dppf<0x140>(db);
;                 const f32x2 sa2 = {da, da}, sb2 = {db, db};
;                 A01 = __builtin_elementwise_fma(A01, w01, __builtin_elementwise_fma(wr01, sa2, vka01)); A23 = __builtin_elementwise_fma(A23, w23, __builtin_elementwise_fma(wr23, sa2, vka23));
;                 B01 = __builtin_elementwise_fma(B01, w01, __builtin_elementwise_fma(wr01, sb2, vkb01)); B23 = __builtin_elementwise_fma(B23, w23, __builtin_elementwise_fma(wr23, sb2, vkb23));
;                 f32x2 ya = A01 * r01; ya = __builtin_elementwise_fma(A23, r23, ya);
.LBB0_726:
	v_readfirstlane_b32 s0, v152
	s_cmpk_lt_u32 s0, 0x100
	s_mov_b64 s[2:3], -1
	s_cbranch_scc0 .LBB0_730
	s_lshr_b32 s0, s0, 3
	v_and_or_b32 v6, s0, 24, v1
	s_setprio 1
	v_mov_b32_e32 v12, 0
	v_lshl_add_u32 v11, v6, 6, v50
	s_mov_b32 s0, 0
	v_mov_b32_e32 v13, v12
	v_mov_b32_e32 v14, v12
	v_mov_b32_e32 v15, v12
	v_mov_b32_e32 v16, v12
	v_mov_b32_e32 v17, v12
	v_mov_b32_e32 v18, v12
	v_mov_b32_e32 v19, v12
	s_and_b32 s2, s0, 1
	s_mul_i32 s3, s2, 0x5800
	s_addk_i32 s3, 0x100
	v_lshl_add_u32 v22, v6, 2, s3
	v_add_u32_e32 v21, s3, v3
	v_lshl_add_u32 v23, s2, 15, v11
	v_add_u32_e32 v20, 0xb000, v23
	s_waitcnt vmcnt(0)
	s_barrier
.LBB0_728:
	ds_read_b128 v[28:31], v21 offset:256
	ds_read_b128 v[36:39], v21 offset:768
	v_add_u32_e32 v23, 0x500, v22
	ds_read2_b32 v[44:45], v23 offset1:4
	ds_read_b128 v[24:27], v21 offset:0
	ds_read_b128 v[32:35], v21 offset:512
	ds_read_b128 v[40:43], v21 offset:1024
	ds_read_b128 v[68:71], v21 offset:1664
	ds_read_b128 v[76:79], v21 offset:2176
	v_add_u32_e32 v23, 0xa80, v22
	ds_read2_b32 v[84:85], v23 offset1:4
	ds_read_b128 v[64:67], v21 offset:1408
	ds_read_b128 v[72:75], v21 offset:1920
	s_waitcnt lgkmcnt(10)
	v_pk_mul_f32 v[46:47], v[12:13], v[28:29] op_sel_hi:[1,0]
	ds_read_b128 v[80:83], v21 offset:2432
	v_pk_fma_f32 v[46:47], v[14:15], v[28:29], v[46:47] op_sel:[0,1,0]
	s_nop 0
	v_pk_fma_f32 v[46:47], v[16:17], v[30:31], v[46:47] op_sel_hi:[1,0,1]
	s_nop 0
	v_pk_fma_f32 v[46:47], v[18:19], v[30:31], v[46:47] op_sel:[0,1,0]
	ds_read_b128 v[28:31], v21 offset:3072
	s_waitcnt lgkmcnt(10)
	v_pk_mul_f32 v[248:249], v[36:37], v[44:45] op_sel_hi:[0,1]
	v_pk_mul_f32 v[250:251], v[36:37], v[44:45] op_sel:[1,0]
	v_add_f32_dpp v46, v46, v46 quad_perm:[1,0,3,2] row_mask:0xf bank_mask:0xf bound_ctrl:1
	v_add_f32_dpp v47, v47, v47 quad_perm:[1,0,3,2] row_mask:0xf bank_mask:0xf bound_ctrl:1
	v_pk_mul_f32 v[252:253], v[38:39], v[44:45] op_sel_hi:[0,1]
	v_add_f32_dpp v46, v46, v46 quad_perm:[2,3,0,1] row_mask:0xf bank_mask:0xf bound_ctrl:1
	v_add_f32_dpp v47, v47, v47 quad_perm:[2,3,0,1] row_mask:0xf bank_mask:0xf bound_ctrl:1
	v_pk_mul_f32 v[254:255], v[38:39], v[44:45] op_sel:[1,0]
	v_add_f32_dpp v46, v46, v46 row_half_mirror row_mask:0xf bank_mask:0xf bound_ctrl:1
	v_add_f32_dpp v47, v47, v47 row_half_mirror row_mask:0xf bank_mask:0xf bound_ctrl:1
	s_nop 0
	v_add_f32_dpp v46, v46, v46 row_mirror row_mask:0xf bank_mask:0xf bound_ctrl:1
	v_add_f32_dpp v47, v47, v47 row_mirror row_mask:0xf bank_mask:0xf bound_ctrl:1
	ds_read_b128 v[36:39], v21 offset:3584
	s_waitcnt lgkmcnt(9)
	v_pk_fma_f32 v[248:249], v[12:13], v[24:25], v[248:249] op_sel_hi:[1,0,1]
	v_add_u32_e32 v23, 0x1000, v22
	ds_read2_b32 v[44:45], v23 offset1:4
	v_pk_fma_f32 v[250:251], v[14:15], v[24:25], v[250:251] op_sel:[0,1,0]
	v_pk_fma_f32 v[252:253], v[16:17], v[26:27], v[252:253] op_sel_hi:[1,0,1]
	v_pk_fma_f32 v[254:255], v[18:19], v[26:27], v[254:255] op_sel:[0,1,0]
	ds_read_b128 v[24:27], v21 offset:2816
	v_pk_fma_f32 v[12:13], v[32:33], v[46:47], v[248:249] op_sel_hi:[0,1,1]
	v_pk_fma_f32 v[14:15], v[32:33], v[46:47], v[250:251] op_sel:[1,0,0]
	v_pk_fma_f32 v[16:17], v[34:35], v[46:47], v[252:253] op_sel_hi:[0,1,1]
	v_pk_fma_f32 v[18:19], v[34:35], v[46:47], v[254:255] op_sel:[1,0,0]
	ds_read_b128 v[32:35], v21 offset:3328
	s_waitcnt lgkmcnt(8)
	v_pk_mul_f32 v[46:47], v[12:13], v[68:69] op_sel_hi:[1,0]
	v_pk_mul_f32 v[48:49], v[12:13], v[40:41] op_sel_hi:[1,0]
	v_pk_fma_f32 v[46:47], v[14:15], v[68:69], v[46:47] op_sel:[0,1,0]
	v_pk_fma_f32 v[48:49], v[14:15], v[40:41], v[48:49] op_sel:[0,1,0]
	v_pk_fma_f32 v[46:47], v[16:17], v[70:71], v[46:47] op_sel_hi:[1,0,1]
	v_pk_fma_f32 v[48:49], v[16:17], v[42:43], v[48:49] op_sel_hi:[1,0,1]
	v_pk_fma_f32 v[46:47], v[18:19], v[70:71], v[46:47] op_sel:[0,1,0]
	v_pk_fma_f32 v[48:49], v[18:19], v[42:43], v[48:49] op_sel:[0,1,0]
	ds_read_b128 v[68:71], v21 offset:4480
	v_pk_mul_f32 v[248:249], v[76:77], v[84:85] op_sel_hi:[0,1]
	v_pk_mul_f32 v[250:251], v[76:77], v[84:85] op_sel:[1,0]
	v_add_f32_dpp v46, v46, v46 quad_perm:[1,0,3,2] row_mask:0xf bank_mask:0xf bound_ctrl:1
	v_add_f32_dpp v47, v47, v47 quad_perm:[1,0,3,2] row_mask:0xf bank_mask:0xf bound_ctrl:1
	ds_write2st64_b32 v20, v48, v49 offset0:0 offset1:1
	v_add_f32_dpp v46, v46, v46 quad_perm:[2,3,0,1] row_mask:0xf bank_mask:0xf bound_ctrl:1
	v_add_f32_dpp v47, v47, v47 quad_perm:[2,3,0,1] row_mask:0xf bank_mask:0xf bound_ctrl:1
	ds_read_b128 v[40:43], v21 offset:3840
	v_add_f32_dpp v46, v46, v46 row_half_mirror row_mask:0xf bank_mask:0xf bound_ctrl:1
	v_add_f32_dpp v47, v47, v47 row_half_mirror row_mask:0xf bank_mask:0xf bound_ctrl:1
	v_pk_mul_f32 v[252:253], v[78:79], v[84:85] op_sel_hi:[0,1]
	v_add_f32_dpp v46, v46, v46 row_mirror row_mask:0xf bank_mask:0xf bound_ctrl:1
	v_add_f32_dpp v47, v47, v47 row_mirror row_mask:0xf bank_mask:0xf bound_ctrl:1
	v_pk_mul_f32 v[254:255], v[78:79], v[84:85] op_sel:[1,0]
	ds_read_b128 v[76:79], v21 offset:4992
	s_waitcnt lgkmcnt(9)
	v_pk_fma_f32 v[248:249], v[12:13], v[64:65], v[248:249] op_sel_hi:[1,0,1]
	v_add_u32_e32 v23, 0x1580, v22
	ds_read2_b32 v[84:85], v23 offset1:4
	v_pk_fma_f32 v[250:251], v[14:15], v[64:65], v[250:251] op_sel:[0,1,0]
	v_pk_fma_f32 v[252:253], v[16:17], v[66:67], v[252:253] op_sel_hi:[1,0,1]
	v_pk_fma_f32 v[254:255], v[18:19], v[66:67], v[254:255] op_sel:[0,1,0]
	ds_read_b128 v[64:67], v21 offset:4224
	v_pk_fma_f32 v[12:13], v[72:73], v[46:47], v[248:249] op_sel_hi:[0,1,1]
	v_pk_fma_f32 v[14:15], v[72:73], v[46:47], v[250:251] op_sel:[1,0,0]
	v_pk_fma_f32 v[16:17], v[74:75], v[46:47], v[252:253] op_sel_hi:[0,1,1]
	v_pk_fma_f32 v[18:19], v[74:75], v[46:47], v[254:255] op_sel:[1,0,0]
	ds_read_b128 v[72:75], v21 offset:4736
	s_waitcnt lgkmcnt(9)
; template <int CTRL> __device__ __forceinline__ float dppf(float x) { return __builtin_bit_cast(float, __builtin_amdgcn_update_dpp(0, __builtin_bit_cast(int, x), CTRL, 0xf, 0xf, true)); }
; __device__ __forceinline__ void scan_item(LAS unsigned char* lds, const ScanPtrs& P, bf16* YC, int item, unsigned* half_cnt, unsigned half_expect) {
;     ...
;             for (int s = 0; s < SC_TC; ++s) {
;                 if (s + 1 < SC_TC) SC_RD(s + 1, nw, nm, nwr, nk, nr, nva, nvb);
;                 __builtin_amdgcn_sched_barrier(0);
;                 const f32x2 m01 = {cm[0], cm[1]}, m23 = {cm[2], cm[3]}, w01 = {cw[0], cw[1]}, w23 = {cw[2], cw[3]}, wr01 = {cwr[0], cwr[1]}, wr23 = {cwr[2], cwr[3]},
;                             k01 = {ck[0], ck[1]}, k23 = {ck[2], ck[3]}, r01 = {cr[0], cr[1]}, r23 = {cr[2], cr[3]};
;                 f32x2 qa = A01 * m01; qa = __builtin_elementwise_fma(A23, m23, qa);
;                 f32x2 qb = B01 * m01; qb = __builtin_elementwise_fma(B23, m23, qb);
;                 float da = qa[0] + qa[1], db = qb[0] + qb[1];
;                 const f32x2 vka01 = k01 * cva, vka23 = k23 * cva, vkb01 = k01 * cvb, vkb23 = k23 * cvb;
;                 da += dppf<0xB1>(da);  db += dppf<0xB1>(db);
;                 da += dppf<0x4E>(da);  db += dppf<0x4E>(db);
;                 da += dppf<0x141>(da); db += dppf<0x141>(db);
;                 da += dppf<0x140>(da); db += dppf<0x140>(db);
;                 const f32x2 sa2 = {da, da}, sb2 = {db, db};
;                 A01 = __builtin_elementwise_fma(A01, w01, __builtin_elementwise_fma(wr01, sa2, vka01)); A23 = __builtin_elementwise_fma(A23, w23, __builtin_elementwise_fma(wr23, sa2, vka23));
;                 B01 = __builtin_elementwise_fma(B01, w01, __builtin_elementwise_fma(wr01, sb2, vkb01)); B23 = __builtin_elementwise_fma(B23, w23, __builtin_elementwise_fma(wr23, sb2, vkb23));
;                 f32x2 ya = A01 * r01; ya = __builtin_elementwise_fma(A23, r23, ya);
;                 f32x2 yb = B01 * r01; yb = __builtin_elementwise_fma(B23, r23, yb);
;                 Y[s * 512] = ya[0] + ya[1]; Y[s * 512 + 64] = yb[0] + yb[1];
;                 __builtin_amdgcn_sched_barrier(0);
;                 cw = nw; cm = nm; cwr = nwr; ck = nk; cr = nr; cva = nva; cvb = nvb;
;             }
	v_pk_mul_f32 v[46:47], v[12:13], v[28:29] op_sel_hi:[1,0]
	v_pk_mul_f32 v[48:49], v[12:13], v[80:81] op_sel_hi:[1,0]
	v_pk_fma_f32 v[46:47], v[14:15], v[28:29], v[46:47] op_sel:[0,1,0]
	v_pk_fma_f32 v[48:49], v[14:15], v[80:81], v[48:49] op_sel:[0,1,0]
	v_pk_fma_f32 v[46:47], v[16:17], v[30:31], v[46:47] op_sel_hi:[1,0,1]
	v_pk_fma_f32 v[48:49], v[16:17], v[82:83], v[48:49] op_sel_hi:[1,0,1]
	v_pk_fma_f32 v[46:47], v[18:19], v[30:31], v[46:47] op_sel:[0,1,0]
	v_pk_fma_f32 v[48:49], v[18:19], v[82:83], v[48:49] op_sel:[0,1,0]
	ds_read_b128 v[28:31], v21 offset:5888
	v_pk_mul_f32 v[248:249], v[36:37], v[44:45] op_sel_hi:[0,1]
	v_pk_mul_f32 v[250:251], v[36:37], v[44:45] op_sel:[1,0]
	v_add_f32_dpp v46, v46, v46 quad_perm:[1,0,3,2] row_mask:0xf bank_mask:0xf bound_ctrl:1
	v_add_f32_dpp v47, v47, v47 quad_perm:[1,0,3,2] row_mask:0xf bank_mask:0xf bound_ctrl:1
	ds_write2st64_b32 v20, v48, v49 offset0:8 offset1:9
	v_add_f32_dpp v46, v46, v46 quad_perm:[2,3,0,1] row_mask:0xf bank_mask:0xf bound_ctrl:1
	v_add_f32_dpp v47, v47, v47 quad_perm:[2,3,0,1] row_mask:0xf bank_mask:0xf bound_ctrl:1
	ds_read_b128 v[80:83], v21 offset:5248
	v_add_f32_dpp v46, v46, v46 row_half_mirror row_mask:0xf bank_mask:0xf bound_ctrl:1
	v_add_f32_dpp v47, v47, v47 row_half_mirror row_mask:0xf bank_mask:0xf bound_ctrl:1
	v_pk_mul_f32 v[252:253], v[38:39], v[44:45] op_sel_hi:[0,1]
	v_add_f32_dpp v46, v46, v46 row_mirror row_mask:0xf bank_mask:0xf bound_ctrl:1
	v_add_f32_dpp v47, v47, v47 row_mirror row_mask:0xf bank_mask:0xf bound_ctrl:1
	v_pk_mul_f32 v[254:255], v[38:39], v[44:45] op_sel:[1,0]
	ds_read_b128 v[36:39], v21 offset:6400
	s_waitcnt lgkmcnt(9)
	v_pk_fma_f32 v[248:249], v[12:13], v[24:25], v[248:249] op_sel_hi:[1,0,1]
	v_add_u32_e32 v23, 0x1b00, v22
	ds_read2_b32 v[44:45], v23 offset1:4
	v_pk_fma_f32 v[250:251], v[14:15], v[24:25], v[250:251] op_sel:[0,1,0]
	v_pk_fma_f32 v[252:253], v[16:17], v[26:27], v[252:253] op_sel_hi:[1,0,1]
	v_pk_fma_f32 v[254:255], v[18:19], v[26:27], v[254:255] op_sel:[0,1,0]
	ds_read_b128 v[24:27], v21 offset:5632
	v_pk_fma_f32 v[12:13], v[32:33], v[46:47], v[248:249] op_sel_hi:[0,1,1]
	v_pk_fma_f32 v[14:15], v[32:33], v[46:47], v[250:251] op_sel:[1,0,0]
	v_pk_fma_f32 v[16:17], v[34:35], v[46:47], v[252:253] op_sel_hi:[0,1,1]
	v_pk_fma_f32 v[18:19], v[34:35], v[46:47], v[254:255] op_sel:[1,0,0]
	ds_read_b128 v[32:35], v21 offset:6144
	s_waitcnt lgkmcnt(9)
	v_pk_mul_f32 v[46:47], v[12:13], v[68:69] op_sel_hi:[1,0]
	v_pk_mul_f32 v[48:49], v[12:13], v[40:41] op_sel_hi:[1,0]
	v_pk_fma_f32 v[46:47], v[14:15], v[68:69], v[46:47] op_sel:[0,1,0]
	v_pk_fma_f32 v[48:49], v[14:15], v[40:41], v[48:49] op_sel:[0,1,0]
	v_pk_fma_f32 v[46:47], v[16:17], v[70:71], v[46:47] op_sel_hi:[1,0,1]
	v_pk_fma_f32 v[48:49], v[16:17], v[42:43], v[48:49] op_sel_hi:[1,0,1]
	v_pk_fma_f32 v[46:47], v[18:19], v[70:71], v[46:47] op_sel:[0,1,0]
	v_pk_fma_f32 v[48:49], v[18:19], v[42:43], v[48:49] op_sel:[0,1,0]
	ds_read_b128 v[68:71], v21 offset:7296
	v_pk_mul_f32 v[248:249], v[76:77], v[84:85] op_sel_hi:[0,1]
	v_pk_mul_f32 v[250:251], v[76:77], v[84:85] op_sel:[1,0]
	v_add_f32_dpp v46, v46, v46 quad_perm:[1,0,3,2] row_mask:0xf bank_mask:0xf bound_ctrl:1
	v_add_f32_dpp v47, v47, v47 quad_perm:[1,0,3,2] row_mask:0xf bank_mask:0xf bound_ctrl:1
	ds_write2st64_b32 v20, v48, v49 offset0:16 offset1:17
	v_add_f32_dpp v46, v46, v46 quad_perm:[2,3,0,1] row_mask:0xf bank_mask:0xf bound_ctrl:1
	v_add_f32_dpp v47, v47, v47 quad_perm:[2,3,0,1] row_mask:0xf bank_mask:0xf bound_ctrl:1
	ds_read_b128 v[40:43], v21 offset:6656
	v_add_f32_dpp v46, v46, v46 row_half_mirror row_mask:0xf bank_mask:0xf bound_ctrl:1
	v_add_f32_dpp v47, v47, v47 row_half_mirror row_mask:0xf bank_mask:0xf bound_ctrl:1
	v_pk_mul_f32 v[252:253], v[78:79], v[84:85] op_sel_hi:[0,1]
	v_add_f32_dpp v46, v46, v46 row_mirror row_mask:0xf bank_mask:0xf bound_ctrl:1
	v_add_f32_dpp v47, v47, v47 row_mirror row_mask:0xf bank_mask:0xf bound_ctrl:1
	v_pk_mul_f32 v[254:255], v[78:79], v[84:85] op_sel:[1,0]
	ds_read_b128 v[76:79], v21 offset:7808
	s_waitcnt lgkmcnt(9)
	v_pk_fma_f32 v[248:249], v[12:13], v[64:65], v[248:249] op_sel_hi:[1,0,1]
	v_add_u32_e32 v23, 0x2080, v22
	ds_read2_b32 v[84:85], v23 offset1:4
	v_pk_fma_f32 v[250:251], v[14:15], v[64:65], v[250:251] op_sel:[0,1,0]
	v_pk_fma_f32 v[252:253], v[16:17], v[66:67], v[252:253] op_sel_hi:[1,0,1]
	v_pk_fma_f32 v[254:255], v[18:19], v[66:67], v[254:255] op_sel:[0,1,0]
	ds_read_b128 v[64:67], v21 offset:7040
	v_pk_fma_f32 v[12:13], v[72:73], v[46:47], v[248:249] op_sel_hi:[0,1,1]
	v_pk_fma_f32 v[14:15], v[72:73], v[46:47], v[250:251] op_sel:[1,0,0]
	v_pk_fma_f32 v[16:17], v[74:75], v[46:47], v[252:253] op_sel_hi:[0,1,1]
	v_pk_fma_f32 v[18:19], v[74:75], v[46:47], v[254:255] op_sel:[1,0,0]
	ds_read_b128 v[72:75], v21 offset:7552
	s_waitcnt lgkmcnt(9)
	v_pk_mul_f32 v[46:47], v[12:13], v[28:29] op_sel_hi:[1,0]
	v_pk_mul_f32 v[48:49], v[12:13], v[80:81] op_sel_hi:[1,0]
	v_pk_fma_f32 v[46:47], v[14:15], v[28:29], v[46:47] op_sel:[0,1,0]
	v_pk_fma_f32 v[48:49], v[14:15], v[80:81], v[48:49] op_sel:[0,1,0]
	v_pk_fma_f32 v[46:47], v[16:17], v[30:31], v[46:47] op_sel_hi:[1,0,1]
	v_pk_fma_f32 v[48:49], v[16:17], v[82:83], v[48:49] op_sel_hi:[1,0,1]
	v_pk_fma_f32 v[46:47], v[18:19], v[30:31], v[46:47] op_sel:[0,1,0]
	v_pk_fma_f32 v[48:49], v[18:19], v[82:83], v[48:49] op_sel:[0,1,0]
	ds_read_b128 v[28:31], v21 offset:8704
	v_pk_mul_f32 v[248:249], v[36:37], v[44:45] op_sel_hi:[0,1]
	v_pk_mul_f32 v[250:251], v[36:37], v[44:45] op_sel:[1,0]
	v_add_f32_dpp v46, v46, v46 quad_perm:[1,0,3,2] row_mask:0xf bank_mask:0xf bound_ctrl:1
	v_add_f32_dpp v47, v47, v47 quad_perm:[1,0,3,2] row_mask:0xf bank_mask:0xf bound_ctrl:1
	ds_write2st64_b32 v20, v48, v49 offset0:24 offset1:25
	v_add_f32_dpp v46, v46, v46 quad_perm:[2,3,0,1] row_mask:0xf bank_mask:0xf bound_ctrl:1
	v_add_f32_dpp v47, v47, v47 quad_perm:[2,3,0,1] row_mask:0xf bank_mask:0xf bound_ctrl:1
	ds_read_b128 v[80:83], v21 offset:8064
	v_add_f32_dpp v46, v46, v46 row_half_mirror row_mask:0xf bank_mask:0xf bound_ctrl:1
	v_add_f32_dpp v47, v47, v47 row_half_mirror row_mask:0xf bank_mask:0xf bound_ctrl:1
	v_pk_mul_f32 v[252:253], v[38:39], v[44:45] op_sel_hi:[0,1]
	v_add_f32_dpp v46, v46, v46 row_mirror row_mask:0xf bank_mask:0xf bound_ctrl:1
	v_add_f32_dpp v47, v47, v47 row_mirror row_mask:0xf bank_mask:0xf bound_ctrl:1
	v_pk_mul_f32 v[254:255], v[38:39], v[44:45] op_sel:[1,0]
	ds_read_b128 v[36:39], v21 offset:9216
	s_waitcnt lgkmcnt(9)
; template <int CTRL> __device__ __forceinline__ float dppf(float x) { return __builtin_bit_cast(float, __builtin_amdgcn_update_dpp(0, __builtin_bit_cast(int, x), CTRL, 0xf, 0xf, true)); }
; __device__ __forceinline__ void scan_item(LAS unsigned char* lds, const ScanPtrs& P, bf16* YC, int item, unsigned* half_cnt, unsigned half_expect) {
;     ...
;             for (int s = 0; s < SC_TC; ++s) {
;                 if (s + 1 < SC_TC) SC_RD(s + 1, nw, nm, nwr, nk, nr, nva, nvb);
;                 __builtin_amdgcn_sched_barrier(0);
;                 const f32x2 m01 = {cm[0], cm[1]}, m23 = {cm[2], cm[3]}, w01 = {cw[0], cw[1]}, w23 = {cw[2], cw[3]}, wr01 = {cwr[0], cwr[1]}, wr23 = {cwr[2], cwr[3]},
;                             k01 = {ck[0], ck[1]}, k23 = {ck[2], ck[3]}, r01 = {cr[0], cr[1]}, r23 = {cr[2], cr[3]};
;                 f32x2 qa = A01 * m01; qa = __builtin_elementwise_fma(A23, m23, qa);
;                 f32x2 qb = B01 * m01; qb = __builtin_elementwise_fma(B23, m23, qb);
;                 float da = qa[0] + qa[1], db = qb[0] + qb[1];
;                 const f32x2 vka01 = k01 * cva, vka23 = k23 * cva, vkb01 = k01 * cvb, vkb23 = k23 * cvb;
;                 da += dppf<0xB1>(da);  db += dppf<0xB1>(db);
;                 da += dppf<0x4E>(da);  db += dppf<0x4E>(db);
;                 da += dppf<0x141>(da); db += dppf<0x141>(db);
;                 da += dppf<0x140>(da); db += dppf<0x140>(db);
;                 const f32x2 sa2 = {da, da}, sb2 = {db, db};
;                 A01 = __builtin_elementwise_fma(A01, w01, __builtin_elementwise_fma(wr01, sa2, vka01)); A23 = __builtin_elementwise_fma(A23, w23, __builtin_elementwise_fma(wr23, sa2, vka23));
;                 B01 = __builtin_elementwise_fma(B01, w01, __builtin_elementwise_fma(wr01, sb2, vkb01)); B23 = __builtin_elementwise_fma(B23, w23, __builtin_elementwise_fma(wr23, sb2, vkb23));
;                 f32x2 ya = A01 * r01; ya = __builtin_elementwise_fma(A23, r23, ya);
;                 f32x2 yb = B01 * r01; yb = __builtin_elementwise_fma(B23, r23, yb);
;                 Y[s * 512] = ya[0] + ya[1]; Y[s * 512 + 64] = yb[0] + yb[1];
;                 __builtin_amdgcn_sched_barrier(0);
;                 cw = nw; cm = nm; cwr = nwr; ck = nk; cr = nr; cva = nva; cvb = nvb;
;             }
	v_pk_fma_f32 v[248:249], v[12:13], v[24:25], v[248:249] op_sel_hi:[1,0,1]
	v_add_u32_e32 v23, 0x2600, v22
	ds_read2_b32 v[44:45], v23 offset1:4
	v_pk_fma_f32 v[250:251], v[14:15], v[24:25], v[250:251] op_sel:[0,1,0]
	v_pk_fma_f32 v[252:253], v[16:17], v[26:27], v[252:253] op_sel_hi:[1,0,1]
	v_pk_fma_f32 v[254:255], v[18:19], v[26:27], v[254:255] op_sel:[0,1,0]
	ds_read_b128 v[24:27], v21 offset:8448
	v_pk_fma_f32 v[12:13], v[32:33], v[46:47], v[248:249] op_sel_hi:[0,1,1]
	v_pk_fma_f32 v[14:15], v[32:33], v[46:47], v[250:251] op_sel:[1,0,0]
	v_pk_fma_f32 v[16:17], v[34:35], v[46:47], v[252:253] op_sel_hi:[0,1,1]
	v_pk_fma_f32 v[18:19], v[34:35], v[46:47], v[254:255] op_sel:[1,0,0]
	ds_read_b128 v[32:35], v21 offset:8960
	s_waitcnt lgkmcnt(9)
	v_pk_mul_f32 v[46:47], v[12:13], v[68:69] op_sel_hi:[1,0]
	v_pk_mul_f32 v[48:49], v[12:13], v[40:41] op_sel_hi:[1,0]
	v_pk_fma_f32 v[46:47], v[14:15], v[68:69], v[46:47] op_sel:[0,1,0]
	v_pk_fma_f32 v[48:49], v[14:15], v[40:41], v[48:49] op_sel:[0,1,0]
	v_pk_fma_f32 v[46:47], v[16:17], v[70:71], v[46:47] op_sel_hi:[1,0,1]
	v_pk_fma_f32 v[48:49], v[16:17], v[42:43], v[48:49] op_sel_hi:[1,0,1]
	v_pk_fma_f32 v[46:47], v[18:19], v[70:71], v[46:47] op_sel:[0,1,0]
	v_pk_fma_f32 v[48:49], v[18:19], v[42:43], v[48:49] op_sel:[0,1,0]
	ds_read_b128 v[68:71], v21 offset:10112
	v_pk_mul_f32 v[248:249], v[76:77], v[84:85] op_sel_hi:[0,1]
	v_pk_mul_f32 v[250:251], v[76:77], v[84:85] op_sel:[1,0]
	v_add_f32_dpp v46, v46, v46 quad_perm:[1,0,3,2] row_mask:0xf bank_mask:0xf bound_ctrl:1
	v_add_f32_dpp v47, v47, v47 quad_perm:[1,0,3,2] row_mask:0xf bank_mask:0xf bound_ctrl:1
	ds_write2st64_b32 v20, v48, v49 offset0:32 offset1:33
	v_add_f32_dpp v46, v46, v46 quad_perm:[2,3,0,1] row_mask:0xf bank_mask:0xf bound_ctrl:1
	v_add_f32_dpp v47, v47, v47 quad_perm:[2,3,0,1] row_mask:0xf bank_mask:0xf bound_ctrl:1
	ds_read_b128 v[40:43], v21 offset:9472
	v_add_f32_dpp v46, v46, v46 row_half_mirror row_mask:0xf bank_mask:0xf bound_ctrl:1
	v_add_f32_dpp v47, v47, v47 row_half_mirror row_mask:0xf bank_mask:0xf bound_ctrl:1
	v_pk_mul_f32 v[252:253], v[78:79], v[84:85] op_sel_hi:[0,1]
	v_add_f32_dpp v46, v46, v46 row_mirror row_mask:0xf bank_mask:0xf bound_ctrl:1
	v_add_f32_dpp v47, v47, v47 row_mirror row_mask:0xf bank_mask:0xf bound_ctrl:1
	v_pk_mul_f32 v[254:255], v[78:79], v[84:85] op_sel:[1,0]
	ds_read_b128 v[76:79], v21 offset:10624
	s_waitcnt lgkmcnt(9)
	v_pk_fma_f32 v[248:249], v[12:13], v[64:65], v[248:249] op_sel_hi:[1,0,1]
	v_add_u32_e32 v23, 0x2b80, v22
	ds_read2_b32 v[84:85], v23 offset1:4
	v_pk_fma_f32 v[250:251], v[14:15], v[64:65], v[250:251] op_sel:[0,1,0]
	v_pk_fma_f32 v[252:253], v[16:17], v[66:67], v[252:253] op_sel_hi:[1,0,1]
	v_pk_fma_f32 v[254:255], v[18:19], v[66:67], v[254:255] op_sel:[0,1,0]
	ds_read_b128 v[64:67], v21 offset:9856
	v_pk_fma_f32 v[12:13], v[72:73], v[46:47], v[248:249] op_sel_hi:[0,1,1]
	v_pk_fma_f32 v[14:15], v[72:73], v[46:47], v[250:251] op_sel:[1,0,0]
	v_pk_fma_f32 v[16:17], v[74:75], v[46:47], v[252:253] op_sel_hi:[0,1,1]
	v_pk_fma_f32 v[18:19], v[74:75], v[46:47], v[254:255] op_sel:[1,0,0]
	ds_read_b128 v[72:75], v21 offset:10368
	s_waitcnt lgkmcnt(9)
	v_pk_mul_f32 v[46:47], v[12:13], v[28:29] op_sel_hi:[1,0]
	v_pk_mul_f32 v[48:49], v[12:13], v[80:81] op_sel_hi:[1,0]
	v_pk_fma_f32 v[46:47], v[14:15], v[28:29], v[46:47] op_sel:[0,1,0]
	v_pk_fma_f32 v[48:49], v[14:15], v[80:81], v[48:49] op_sel:[0,1,0]
	v_pk_fma_f32 v[46:47], v[16:17], v[30:31], v[46:47] op_sel_hi:[1,0,1]
	v_pk_fma_f32 v[48:49], v[16:17], v[82:83], v[48:49] op_sel_hi:[1,0,1]
	v_pk_fma_f32 v[46:47], v[18:19], v[30:31], v[46:47] op_sel:[0,1,0]
	v_pk_fma_f32 v[48:49], v[18:19], v[82:83], v[48:49] op_sel:[0,1,0]
	ds_read_b128 v[28:31], v21 offset:11520
	v_pk_mul_f32 v[248:249], v[36:37], v[44:45] op_sel_hi:[0,1]
	v_pk_mul_f32 v[250:251], v[36:37], v[44:45] op_sel:[1,0]
	v_add_f32_dpp v46, v46, v46 quad_perm:[1,0,3,2] row_mask:0xf bank_mask:0xf bound_ctrl:1
	v_add_f32_dpp v47, v47, v47 quad_perm:[1,0,3,2] row_mask:0xf bank_mask:0xf bound_ctrl:1
	ds_write2st64_b32 v20, v48, v49 offset0:40 offset1:41
	v_add_f32_dpp v46, v46, v46 quad_perm:[2,3,0,1] row_mask:0xf bank_mask:0xf bound_ctrl:1
	v_add_f32_dpp v47, v47, v47 quad_perm:[2,3,0,1] row_mask:0xf bank_mask:0xf bound_ctrl:1
	ds_read_b128 v[80:83], v21 offset:10880
	v_add_f32_dpp v46, v46, v46 row_half_mirror row_mask:0xf bank_mask:0xf bound_ctrl:1
	v_add_f32_dpp v47, v47, v47 row_half_mirror row_mask:0xf bank_mask:0xf bound_ctrl:1
	v_pk_mul_f32 v[252:253], v[38:39], v[44:45] op_sel_hi:[0,1]
	v_add_f32_dpp v46, v46, v46 row_mirror row_mask:0xf bank_mask:0xf bound_ctrl:1
	v_add_f32_dpp v47, v47, v47 row_mirror row_mask:0xf bank_mask:0xf bound_ctrl:1
	v_pk_mul_f32 v[254:255], v[38:39], v[44:45] op_sel:[1,0]
	ds_read_b128 v[36:39], v21 offset:12032
	s_waitcnt lgkmcnt(9)
	v_pk_fma_f32 v[248:249], v[12:13], v[24:25], v[248:249] op_sel_hi:[1,0,1]
	v_add_u32_e32 v23, 0x3100, v22
	ds_read2_b32 v[44:45], v23 offset1:4
	v_pk_fma_f32 v[250:251], v[14:15], v[24:25], v[250:251] op_sel:[0,1,0]
	v_pk_fma_f32 v[252:253], v[16:17], v[26:27], v[252:253] op_sel_hi:[1,0,1]
	v_pk_fma_f32 v[254:255], v[18:19], v[26:27], v[254:255] op_sel:[0,1,0]
	ds_read_b128 v[24:27], v21 offset:11264
	v_pk_fma_f32 v[12:13], v[32:33], v[46:47], v[248:249] op_sel_hi:[0,1,1]
	v_pk_fma_f32 v[14:15], v[32:33], v[46:47], v[250:251] op_sel:[1,0,0]
	v_pk_fma_f32 v[16:17], v[34:35], v[46:47], v[252:253] op_sel_hi:[0,1,1]
	v_pk_fma_f32 v[18:19], v[34:35], v[46:47], v[254:255] op_sel:[1,0,0]
	ds_read_b128 v[32:35], v21 offset:11776
	s_waitcnt lgkmcnt(9)
; template <int CTRL> __device__ __forceinline__ float dppf(float x) { return __builtin_bit_cast(float, __builtin_amdgcn_update_dpp(0, __builtin_bit_cast(int, x), CTRL, 0xf, 0xf, true)); }
; __device__ __forceinline__ void scan_item(LAS unsigned char* lds, const ScanPtrs& P, bf16* YC, int item, unsigned* half_cnt, unsigned half_expect) {
;     ...
;             for (int s = 0; s < SC_TC; ++s) {
;                 if (s + 1 < SC_TC) SC_RD(s + 1, nw, nm, nwr, nk, nr, nva, nvb);
;                 __builtin_amdgcn_sched_barrier(0);
;                 const f32x2 m01 = {cm[0], cm[1]}, m23 = {cm[2], cm[3]}, w01 = {cw[0], cw[1]}, w23 = {cw[2], cw[3]}, wr01 = {cwr[0], cwr[1]}, wr23 = {cwr[2], cwr[3]},
;                             k01 = {ck[0], ck[1]}, k23 = {ck[2], ck[3]}, r01 = {cr[0], cr[1]}, r23 = {cr[2], cr[3]};
;                 f32x2 qa = A01 * m01; qa = __builtin_elementwise_fma(A23, m23, qa);
;                 f32x2 qb = B01 * m01; qb = __builtin_elementwise_fma(B23, m23, qb);
;                 float da = qa[0] + qa[1], db = qb[0] + qb[1];
;                 const f32x2 vka01 = k01 * cva, vka23 = k23 * cva, vkb01 = k01 * cvb, vkb23 = k23 * cvb;
;                 da += dppf<0xB1>(da);  db += dppf<0xB1>(db);
;                 da += dppf<0x4E>(da);  db += dppf<0x4E>(db);
;                 da += dppf<0x141>(da); db += dppf<0x141>(db);
;                 da += dppf<0x140>(da); db += dppf<0x140>(db);
;                 const f32x2 sa2 = {da, da}, sb2 = {db, db};
;                 A01 = __builtin_elementwise_fma(A01, w01, __builtin_elementwise_fma(wr01, sa2, vka01)); A23 = __builtin_elementwise_fma(A23, w23, __builtin_elementwise_fma(wr23, sa2, vka23));
;                 B01 = __builtin_elementwise_fma(B01, w01, __builtin_elementwise_fma(wr01, sb2, vkb01)); B23 = __builtin_elementwise_fma(B23, w23, __builtin_elementwise_fma(wr23, sb2, vkb23));
;                 f32x2 ya = A01 * r01; ya = __builtin_elementwise_fma(A23, r23, ya);
;                 f32x2 yb = B01 * r01; yb = __builtin_elementwise_fma(B23, r23, yb);
;                 Y[s * 512] = ya[0] + ya[1]; Y[s * 512 + 64] = yb[0] + yb[1];
;                 __builtin_amdgcn_sched_barrier(0);
;                 cw = nw; cm = nm; cwr = nwr; ck = nk; cr = nr; cva = nva; cvb = nvb;
;             }
	v_pk_mul_f32 v[46:47], v[12:13], v[68:69] op_sel_hi:[1,0]
	v_pk_mul_f32 v[48:49], v[12:13], v[40:41] op_sel_hi:[1,0]
	v_pk_fma_f32 v[46:47], v[14:15], v[68:69], v[46:47] op_sel:[0,1,0]
	v_pk_fma_f32 v[48:49], v[14:15], v[40:41], v[48:49] op_sel:[0,1,0]
	v_pk_fma_f32 v[46:47], v[16:17], v[70:71], v[46:47] op_sel_hi:[1,0,1]
	v_pk_fma_f32 v[48:49], v[16:17], v[42:43], v[48:49] op_sel_hi:[1,0,1]
	v_pk_fma_f32 v[46:47], v[18:19], v[70:71], v[46:47] op_sel:[0,1,0]
	v_pk_fma_f32 v[48:49], v[18:19], v[42:43], v[48:49] op_sel:[0,1,0]
	ds_read_b128 v[68:71], v21 offset:12928
	v_pk_mul_f32 v[248:249], v[76:77], v[84:85] op_sel_hi:[0,1]
	v_pk_mul_f32 v[250:251], v[76:77], v[84:85] op_sel:[1,0]
	v_add_f32_dpp v46, v46, v46 quad_perm:[1,0,3,2] row_mask:0xf bank_mask:0xf bound_ctrl:1
	v_add_f32_dpp v47, v47, v47 quad_perm:[1,0,3,2] row_mask:0xf bank_mask:0xf bound_ctrl:1
	ds_write2st64_b32 v20, v48, v49 offset0:48 offset1:49
	v_add_f32_dpp v46, v46, v46 quad_perm:[2,3,0,1] row_mask:0xf bank_mask:0xf bound_ctrl:1
	v_add_f32_dpp v47, v47, v47 quad_perm:[2,3,0,1] row_mask:0xf bank_mask:0xf bound_ctrl:1
	ds_read_b128 v[40:43], v21 offset:12288
	v_add_f32_dpp v46, v46, v46 row_half_mirror row_mask:0xf bank_mask:0xf bound_ctrl:1
	v_add_f32_dpp v47, v47, v47 row_half_mirror row_mask:0xf bank_mask:0xf bound_ctrl:1
	v_pk_mul_f32 v[252:253], v[78:79], v[84:85] op_sel_hi:[0,1]
	v_add_f32_dpp v46, v46, v46 row_mirror row_mask:0xf bank_mask:0xf bound_ctrl:1
	v_add_f32_dpp v47, v47, v47 row_mirror row_mask:0xf bank_mask:0xf bound_ctrl:1
	v_pk_mul_f32 v[254:255], v[78:79], v[84:85] op_sel:[1,0]
	ds_read_b128 v[76:79], v21 offset:13440
	s_waitcnt lgkmcnt(9)
	v_pk_fma_f32 v[248:249], v[12:13], v[64:65], v[248:249] op_sel_hi:[1,0,1]
	v_add_u32_e32 v23, 0x3680, v22
	ds_read2_b32 v[84:85], v23 offset1:4
	v_pk_fma_f32 v[250:251], v[14:15], v[64:65], v[250:251] op_sel:[0,1,0]
	v_pk_fma_f32 v[252:253], v[16:17], v[66:67], v[252:253] op_sel_hi:[1,0,1]
	v_pk_fma_f32 v[254:255], v[18:19], v[66:67], v[254:255] op_sel:[0,1,0]
	ds_read_b128 v[64:67], v21 offset:12672
	v_pk_fma_f32 v[12:13], v[72:73], v[46:47], v[248:249] op_sel_hi:[0,1,1]
	v_pk_fma_f32 v[14:15], v[72:73], v[46:47], v[250:251] op_sel:[1,0,0]
	v_pk_fma_f32 v[16:17], v[74:75], v[46:47], v[252:253] op_sel_hi:[0,1,1]
	v_pk_fma_f32 v[18:19], v[74:75], v[46:47], v[254:255] op_sel:[1,0,0]
	ds_read_b128 v[72:75], v21 offset:13184
	s_waitcnt lgkmcnt(9)
	v_pk_mul_f32 v[46:47], v[12:13], v[28:29] op_sel_hi:[1,0]
	v_pk_mul_f32 v[48:49], v[12:13], v[80:81] op_sel_hi:[1,0]
	v_pk_fma_f32 v[46:47], v[14:15], v[28:29], v[46:47] op_sel:[0,1,0]
	v_pk_fma_f32 v[48:49], v[14:15], v[80:81], v[48:49] op_sel:[0,1,0]
	v_pk_fma_f32 v[46:47], v[16:17], v[30:31], v[46:47] op_sel_hi:[1,0,1]
	v_pk_fma_f32 v[48:49], v[16:17], v[82:83], v[48:49] op_sel_hi:[1,0,1]
	v_pk_fma_f32 v[46:47], v[18:19], v[30:31], v[46:47] op_sel:[0,1,0]
	v_pk_fma_f32 v[48:49], v[18:19], v[82:83], v[48:49] op_sel:[0,1,0]
	ds_read_b128 v[28:31], v21 offset:14336
	v_pk_mul_f32 v[248:249], v[36:37], v[44:45] op_sel_hi:[0,1]
	v_pk_mul_f32 v[250:251], v[36:37], v[44:45] op_sel:[1,0]
	v_add_f32_dpp v46, v46, v46 quad_perm:[1,0,3,2] row_mask:0xf bank_mask:0xf bound_ctrl:1
	v_add_f32_dpp v47, v47, v47 quad_perm:[1,0,3,2] row_mask:0xf bank_mask:0xf bound_ctrl:1
	ds_write2st64_b32 v20, v48, v49 offset0:56 offset1:57
	v_add_f32_dpp v46, v46, v46 quad_perm:[2,3,0,1] row_mask:0xf bank_mask:0xf bound_ctrl:1
	v_add_f32_dpp v47, v47, v47 quad_perm:[2,3,0,1] row_mask:0xf bank_mask:0xf bound_ctrl:1
	ds_read_b128 v[80:83], v21 offset:13696
	v_add_f32_dpp v46, v46, v46 row_half_mirror row_mask:0xf bank_mask:0xf bound_ctrl:1
	v_add_f32_dpp v47, v47, v47 row_half_mirror row_mask:0xf bank_mask:0xf bound_ctrl:1
	v_pk_mul_f32 v[252:253], v[38:39], v[44:45] op_sel_hi:[0,1]
	v_add_f32_dpp v46, v46, v46 row_mirror row_mask:0xf bank_mask:0xf bound_ctrl:1
	v_add_f32_dpp v47, v47, v47 row_mirror row_mask:0xf bank_mask:0xf bound_ctrl:1
	v_pk_mul_f32 v[254:255], v[38:39], v[44:45] op_sel:[1,0]
	ds_read_b128 v[36:39], v21 offset:14848
	s_waitcnt lgkmcnt(9)
	v_pk_fma_f32 v[248:249], v[12:13], v[24:25], v[248:249] op_sel_hi:[1,0,1]
	v_add_u32_e32 v23, 0x3c00, v22
	ds_read2_b32 v[44:45], v23 offset1:4
	v_pk_fma_f32 v[250:251], v[14:15], v[24:25], v[250:251] op_sel:[0,1,0]
	v_pk_fma_f32 v[252:253], v[16:17], v[26:27], v[252:253] op_sel_hi:[1,0,1]
	v_pk_fma_f32 v[254:255], v[18:19], v[26:27], v[254:255] op_sel:[0,1,0]
	ds_read_b128 v[24:27], v21 offset:14080
	v_pk_fma_f32 v[12:13], v[32:33], v[46:47], v[248:249] op_sel_hi:[0,1,1]
	v_pk_fma_f32 v[14:15], v[32:33], v[46:47], v[250:251] op_sel:[1,0,0]
	v_pk_fma_f32 v[16:17], v[34:35], v[46:47], v[252:253] op_sel_hi:[0,1,1]
	v_pk_fma_f32 v[18:19], v[34:35], v[46:47], v[254:255] op_sel:[1,0,0]
	ds_read_b128 v[32:35], v21 offset:14592
	s_waitcnt lgkmcnt(9)
; template <int CTRL> __device__ __forceinline__ float dppf(float x) { return __builtin_bit_cast(float, __builtin_amdgcn_update_dpp(0, __builtin_bit_cast(int, x), CTRL, 0xf, 0xf, true)); }
; __device__ __forceinline__ void scan_item(LAS unsigned char* lds, const ScanPtrs& P, bf16* YC, int item, unsigned* half_cnt, unsigned half_expect) {
;     ...
;             for (int s = 0; s < SC_TC; ++s) {
;                 if (s + 1 < SC_TC) SC_RD(s + 1, nw, nm, nwr, nk, nr, nva, nvb);
;                 __builtin_amdgcn_sched_barrier(0);
;                 const f32x2 m01 = {cm[0], cm[1]}, m23 = {cm[2], cm[3]}, w01 = {cw[0], cw[1]}, w23 = {cw[2], cw[3]}, wr01 = {cwr[0], cwr[1]}, wr23 = {cwr[2], cwr[3]},
;                             k01 = {ck[0], ck[1]}, k23 = {ck[2], ck[3]}, r01 = {cr[0], cr[1]}, r23 = {cr[2], cr[3]};
;                 f32x2 qa = A01 * m01; qa = __builtin_elementwise_fma(A23, m23, qa);
;                 f32x2 qb = B01 * m01; qb = __builtin_elementwise_fma(B23, m23, qb);
;                 float da = qa[0] + qa[1], db = qb[0] + qb[1];
;                 const f32x2 vka01 = k01 * cva, vka23 = k23 * cva, vkb01 = k01 * cvb, vkb23 = k23 * cvb;
;                 da += dppf<0xB1>(da);  db += dppf<0xB1>(db);
;                 da += dppf<0x4E>(da);  db += dppf<0x4E>(db);
;                 da += dppf<0x141>(da); db += dppf<0x141>(db);
;                 da += dppf<0x140>(da); db += dppf<0x140>(db);
;                 const f32x2 sa2 = {da, da}, sb2 = {db, db};
;                 A01 = __builtin_elementwise_fma(A01, w01, __builtin_elementwise_fma(wr01, sa2, vka01)); A23 = __builtin_elementwise_fma(A23, w23, __builtin_elementwise_fma(wr23, sa2, vka23));
;                 B01 = __builtin_elementwise_fma(B01, w01, __builtin_elementwise_fma(wr01, sb2, vkb01)); B23 = __builtin_elementwise_fma(B23, w23, __builtin_elementwise_fma(wr23, sb2, vkb23));
;                 f32x2 ya = A01 * r01; ya = __builtin_elementwise_fma(A23, r23, ya);
;                 f32x2 yb = B01 * r01; yb = __builtin_elementwise_fma(B23, r23, yb);
;                 Y[s * 512] = ya[0] + ya[1]; Y[s * 512 + 64] = yb[0] + yb[1];
;                 __builtin_amdgcn_sched_barrier(0);
;                 cw = nw; cm = nm; cwr = nwr; ck = nk; cr = nr; cva = nva; cvb = nvb;
;             }
	v_pk_mul_f32 v[46:47], v[12:13], v[68:69] op_sel_hi:[1,0]
	v_pk_mul_f32 v[48:49], v[12:13], v[40:41] op_sel_hi:[1,0]
	v_pk_fma_f32 v[46:47], v[14:15], v[68:69], v[46:47] op_sel:[0,1,0]
	v_pk_fma_f32 v[48:49], v[14:15], v[40:41], v[48:49] op_sel:[0,1,0]
	v_pk_fma_f32 v[46:47], v[16:17], v[70:71], v[46:47] op_sel_hi:[1,0,1]
	v_pk_fma_f32 v[48:49], v[16:17], v[42:43], v[48:49] op_sel_hi:[1,0,1]
	v_pk_fma_f32 v[46:47], v[18:19], v[70:71], v[46:47] op_sel:[0,1,0]
	v_pk_fma_f32 v[48:49], v[18:19], v[42:43], v[48:49] op_sel:[0,1,0]
	ds_read_b128 v[68:71], v21 offset:15744
	v_pk_mul_f32 v[248:249], v[76:77], v[84:85] op_sel_hi:[0,1]
	v_pk_mul_f32 v[250:251], v[76:77], v[84:85] op_sel:[1,0]
	v_add_f32_dpp v46, v46, v46 quad_perm:[1,0,3,2] row_mask:0xf bank_mask:0xf bound_ctrl:1
	v_add_f32_dpp v47, v47, v47 quad_perm:[1,0,3,2] row_mask:0xf bank_mask:0xf bound_ctrl:1
	ds_write2st64_b32 v20, v48, v49 offset0:64 offset1:65
	v_add_f32_dpp v46, v46, v46 quad_perm:[2,3,0,1] row_mask:0xf bank_mask:0xf bound_ctrl:1
	v_add_f32_dpp v47, v47, v47 quad_perm:[2,3,0,1] row_mask:0xf bank_mask:0xf bound_ctrl:1
	ds_read_b128 v[40:43], v21 offset:15104
	v_add_f32_dpp v46, v46, v46 row_half_mirror row_mask:0xf bank_mask:0xf bound_ctrl:1
	v_add_f32_dpp v47, v47, v47 row_half_mirror row_mask:0xf bank_mask:0xf bound_ctrl:1
	v_pk_mul_f32 v[252:253], v[78:79], v[84:85] op_sel_hi:[0,1]
	v_add_f32_dpp v46, v46, v46 row_mirror row_mask:0xf bank_mask:0xf bound_ctrl:1
	v_add_f32_dpp v47, v47, v47 row_mirror row_mask:0xf bank_mask:0xf bound_ctrl:1
	v_pk_mul_f32 v[254:255], v[78:79], v[84:85] op_sel:[1,0]
	ds_read_b128 v[76:79], v21 offset:16256
	s_waitcnt lgkmcnt(9)
	v_pk_fma_f32 v[248:249], v[12:13], v[64:65], v[248:249] op_sel_hi:[1,0,1]
	v_add_u32_e32 v23, 0x4180, v22
	ds_read2_b32 v[84:85], v23 offset1:4
	v_pk_fma_f32 v[250:251], v[14:15], v[64:65], v[250:251] op_sel:[0,1,0]
	v_pk_fma_f32 v[252:253], v[16:17], v[66:67], v[252:253] op_sel_hi:[1,0,1]
	v_pk_fma_f32 v[254:255], v[18:19], v[66:67], v[254:255] op_sel:[0,1,0]
	ds_read_b128 v[64:67], v21 offset:15488
	v_pk_fma_f32 v[12:13], v[72:73], v[46:47], v[248:249] op_sel_hi:[0,1,1]
	v_pk_fma_f32 v[14:15], v[72:73], v[46:47], v[250:251] op_sel:[1,0,0]
	v_pk_fma_f32 v[16:17], v[74:75], v[46:47], v[252:253] op_sel_hi:[0,1,1]
	v_pk_fma_f32 v[18:19], v[74:75], v[46:47], v[254:255] op_sel:[1,0,0]
	ds_read_b128 v[72:75], v21 offset:16000
	s_waitcnt lgkmcnt(9)
	v_pk_mul_f32 v[46:47], v[12:13], v[28:29] op_sel_hi:[1,0]
	v_pk_mul_f32 v[48:49], v[12:13], v[80:81] op_sel_hi:[1,0]
	v_pk_fma_f32 v[46:47], v[14:15], v[28:29], v[46:47] op_sel:[0,1,0]
	v_pk_fma_f32 v[48:49], v[14:15], v[80:81], v[48:49] op_sel:[0,1,0]
	v_pk_fma_f32 v[46:47], v[16:17], v[30:31], v[46:47] op_sel_hi:[1,0,1]
	v_pk_fma_f32 v[48:49], v[16:17], v[82:83], v[48:49] op_sel_hi:[1,0,1]
	v_pk_fma_f32 v[46:47], v[18:19], v[30:31], v[46:47] op_sel:[0,1,0]
	v_pk_fma_f32 v[48:49], v[18:19], v[82:83], v[48:49] op_sel:[0,1,0]
	ds_read_b128 v[28:31], v21 offset:17152
	v_pk_mul_f32 v[248:249], v[36:37], v[44:45] op_sel_hi:[0,1]
	v_pk_mul_f32 v[250:251], v[36:37], v[44:45] op_sel:[1,0]
	v_add_f32_dpp v46, v46, v46 quad_perm:[1,0,3,2] row_mask:0xf bank_mask:0xf bound_ctrl:1
	v_add_f32_dpp v47, v47, v47 quad_perm:[1,0,3,2] row_mask:0xf bank_mask:0xf bound_ctrl:1
	ds_write2st64_b32 v20, v48, v49 offset0:72 offset1:73
	v_add_f32_dpp v46, v46, v46 quad_perm:[2,3,0,1] row_mask:0xf bank_mask:0xf bound_ctrl:1
	v_add_f32_dpp v47, v47, v47 quad_perm:[2,3,0,1] row_mask:0xf bank_mask:0xf bound_ctrl:1
	ds_read_b128 v[80:83], v21 offset:16512
	v_add_f32_dpp v46, v46, v46 row_half_mirror row_mask:0xf bank_mask:0xf bound_ctrl:1
	v_add_f32_dpp v47, v47, v47 row_half_mirror row_mask:0xf bank_mask:0xf bound_ctrl:1
	v_pk_mul_f32 v[252:253], v[38:39], v[44:45] op_sel_hi:[0,1]
	v_add_f32_dpp v46, v46, v46 row_mirror row_mask:0xf bank_mask:0xf bound_ctrl:1
	v_add_f32_dpp v47, v47, v47 row_mirror row_mask:0xf bank_mask:0xf bound_ctrl:1
	v_pk_mul_f32 v[254:255], v[38:39], v[44:45] op_sel:[1,0]
	ds_read_b128 v[36:39], v21 offset:17664
	s_waitcnt lgkmcnt(9)
	v_pk_fma_f32 v[248:249], v[12:13], v[24:25], v[248:249] op_sel_hi:[1,0,1]
	v_add_u32_e32 v23, 0x4700, v22
	ds_read2_b32 v[44:45], v23 offset1:4
	v_pk_fma_f32 v[250:251], v[14:15], v[24:25], v[250:251] op_sel:[0,1,0]
	v_pk_fma_f32 v[252:253], v[16:17], v[26:27], v[252:253] op_sel_hi:[1,0,1]
	v_pk_fma_f32 v[254:255], v[18:19], v[26:27], v[254:255] op_sel:[0,1,0]
	ds_read_b128 v[24:27], v21 offset:16896
	v_pk_fma_f32 v[12:13], v[32:33], v[46:47], v[248:249] op_sel_hi:[0,1,1]
	v_pk_fma_f32 v[14:15], v[32:33], v[46:47], v[250:251] op_sel:[1,0,0]
	v_pk_fma_f32 v[16:17], v[34:35], v[46:47], v[252:253] op_sel_hi:[0,1,1]
	v_pk_fma_f32 v[18:19], v[34:35], v[46:47], v[254:255] op_sel:[1,0,0]
	ds_read_b128 v[32:35], v21 offset:17408
	s_waitcnt lgkmcnt(9)
; template <int CTRL> __device__ __forceinline__ float dppf(float x) { return __builtin_bit_cast(float, __builtin_amdgcn_update_dpp(0, __builtin_bit_cast(int, x), CTRL, 0xf, 0xf, true)); }
; __device__ __forceinline__ void scan_item(LAS unsigned char* lds, const ScanPtrs& P, bf16* YC, int item, unsigned* half_cnt, unsigned half_expect) {
;     ...
;             for (int s = 0; s < SC_TC; ++s) {
;                 if (s + 1 < SC_TC) SC_RD(s + 1, nw, nm, nwr, nk, nr, nva, nvb);
;                 __builtin_amdgcn_sched_barrier(0);
;                 const f32x2 m01 = {cm[0], cm[1]}, m23 = {cm[2], cm[3]}, w01 = {cw[0], cw[1]}, w23 = {cw[2], cw[3]}, wr01 = {cwr[0], cwr[1]}, wr23 = {cwr[2], cwr[3]},
;                             k01 = {ck[0], ck[1]}, k23 = {ck[2], ck[3]}, r01 = {cr[0], cr[1]}, r23 = {cr[2], cr[3]};
;                 f32x2 qa = A01 * m01; qa = __builtin_elementwise_fma(A23, m23, qa);
;                 f32x2 qb = B01 * m01; qb = __builtin_elementwise_fma(B23, m23, qb);
;                 float da = qa[0] + qa[1], db = qb[0] + qb[1];
;                 const f32x2 vka01 = k01 * cva, vka23 = k23 * cva, vkb01 = k01 * cvb, vkb23 = k23 * cvb;
;                 da += dppf<0xB1>(da);  db += dppf<0xB1>(db);
;                 da += dppf<0x4E>(da);  db += dppf<0x4E>(db);
;                 da += dppf<0x141>(da); db += dppf<0x141>(db);
;                 da += dppf<0x140>(da); db += dppf<0x140>(db);
;                 const f32x2 sa2 = {da, da}, sb2 = {db, db};
;                 A01 = __builtin_elementwise_fma(A01, w01, __builtin_elementwise_fma(wr01, sa2, vka01)); A23 = __builtin_elementwise_fma(A23, w23, __builtin_elementwise_fma(wr23, sa2, vka23));
;                 B01 = __builtin_elementwise_fma(B01, w01, __builtin_elementwise_fma(wr01, sb2, vkb01)); B23 = __builtin_elementwise_fma(B23, w23, __builtin_elementwise_fma(wr23, sb2, vkb23));
;                 f32x2 ya = A01 * r01; ya = __builtin_elementwise_fma(A23, r23, ya);
;                 f32x2 yb = B01 * r01; yb = __builtin_elementwise_fma(B23, r23, yb);
;                 Y[s * 512] = ya[0] + ya[1]; Y[s * 512 + 64] = yb[0] + yb[1];
;                 __builtin_amdgcn_sched_barrier(0);
;                 cw = nw; cm = nm; cwr = nwr; ck = nk; cr = nr; cva = nva; cvb = nvb;
;             }
	v_pk_mul_f32 v[46:47], v[12:13], v[68:69] op_sel_hi:[1,0]
	v_pk_mul_f32 v[48:49], v[12:13], v[40:41] op_sel_hi:[1,0]
	v_pk_fma_f32 v[46:47], v[14:15], v[68:69], v[46:47] op_sel:[0,1,0]
	v_pk_fma_f32 v[48:49], v[14:15], v[40:41], v[48:49] op_sel:[0,1,0]
	v_pk_fma_f32 v[46:47], v[16:17], v[70:71], v[46:47] op_sel_hi:[1,0,1]
	v_pk_fma_f32 v[48:49], v[16:17], v[42:43], v[48:49] op_sel_hi:[1,0,1]
	v_pk_fma_f32 v[46:47], v[18:19], v[70:71], v[46:47] op_sel:[0,1,0]
	v_pk_fma_f32 v[48:49], v[18:19], v[42:43], v[48:49] op_sel:[0,1,0]
	ds_read_b128 v[68:71], v21 offset:18560
	v_pk_mul_f32 v[248:249], v[76:77], v[84:85] op_sel_hi:[0,1]
	v_pk_mul_f32 v[250:251], v[76:77], v[84:85] op_sel:[1,0]
	v_add_f32_dpp v46, v46, v46 quad_perm:[1,0,3,2] row_mask:0xf bank_mask:0xf bound_ctrl:1
	v_add_f32_dpp v47, v47, v47 quad_perm:[1,0,3,2] row_mask:0xf bank_mask:0xf bound_ctrl:1
	ds_write2st64_b32 v20, v48, v49 offset0:80 offset1:81
	v_add_f32_dpp v46, v46, v46 quad_perm:[2,3,0,1] row_mask:0xf bank_mask:0xf bound_ctrl:1
	v_add_f32_dpp v47, v47, v47 quad_perm:[2,3,0,1] row_mask:0xf bank_mask:0xf bound_ctrl:1
	ds_read_b128 v[40:43], v21 offset:17920
	v_add_f32_dpp v46, v46, v46 row_half_mirror row_mask:0xf bank_mask:0xf bound_ctrl:1
	v_add_f32_dpp v47, v47, v47 row_half_mirror row_mask:0xf bank_mask:0xf bound_ctrl:1
	v_pk_mul_f32 v[252:253], v[78:79], v[84:85] op_sel_hi:[0,1]
	v_add_f32_dpp v46, v46, v46 row_mirror row_mask:0xf bank_mask:0xf bound_ctrl:1
	v_add_f32_dpp v47, v47, v47 row_mirror row_mask:0xf bank_mask:0xf bound_ctrl:1
	v_pk_mul_f32 v[254:255], v[78:79], v[84:85] op_sel:[1,0]
	ds_read_b128 v[76:79], v21 offset:19072
	s_waitcnt lgkmcnt(9)
	v_pk_fma_f32 v[248:249], v[12:13], v[64:65], v[248:249] op_sel_hi:[1,0,1]
	v_add_u32_e32 v23, 0x4c80, v22
	ds_read2_b32 v[84:85], v23 offset1:4
	v_pk_fma_f32 v[250:251], v[14:15], v[64:65], v[250:251] op_sel:[0,1,0]
	v_pk_fma_f32 v[252:253], v[16:17], v[66:67], v[252:253] op_sel_hi:[1,0,1]
	v_pk_fma_f32 v[254:255], v[18:19], v[66:67], v[254:255] op_sel:[0,1,0]
	ds_read_b128 v[64:67], v21 offset:18304
	v_pk_fma_f32 v[12:13], v[72:73], v[46:47], v[248:249] op_sel_hi:[0,1,1]
	v_pk_fma_f32 v[14:15], v[72:73], v[46:47], v[250:251] op_sel:[1,0,0]
	v_pk_fma_f32 v[16:17], v[74:75], v[46:47], v[252:253] op_sel_hi:[0,1,1]
	v_pk_fma_f32 v[18:19], v[74:75], v[46:47], v[254:255] op_sel:[1,0,0]
	ds_read_b128 v[72:75], v21 offset:18816
	s_waitcnt lgkmcnt(9)
	v_pk_mul_f32 v[46:47], v[12:13], v[28:29] op_sel_hi:[1,0]
	v_pk_mul_f32 v[48:49], v[12:13], v[80:81] op_sel_hi:[1,0]
	v_pk_fma_f32 v[46:47], v[14:15], v[28:29], v[46:47] op_sel:[0,1,0]
	v_pk_fma_f32 v[48:49], v[14:15], v[80:81], v[48:49] op_sel:[0,1,0]
	v_pk_fma_f32 v[46:47], v[16:17], v[30:31], v[46:47] op_sel_hi:[1,0,1]
	v_pk_fma_f32 v[48:49], v[16:17], v[82:83], v[48:49] op_sel_hi:[1,0,1]
	v_pk_fma_f32 v[46:47], v[18:19], v[30:31], v[46:47] op_sel:[0,1,0]
	v_pk_fma_f32 v[48:49], v[18:19], v[82:83], v[48:49] op_sel:[0,1,0]
	ds_read_b128 v[28:31], v21 offset:19968
	v_pk_mul_f32 v[248:249], v[36:37], v[44:45] op_sel_hi:[0,1]
	v_pk_mul_f32 v[250:251], v[36:37], v[44:45] op_sel:[1,0]
	v_add_f32_dpp v46, v46, v46 quad_perm:[1,0,3,2] row_mask:0xf bank_mask:0xf bound_ctrl:1
	v_add_f32_dpp v47, v47, v47 quad_perm:[1,0,3,2] row_mask:0xf bank_mask:0xf bound_ctrl:1
	ds_write2st64_b32 v20, v48, v49 offset0:88 offset1:89
	v_add_f32_dpp v46, v46, v46 quad_perm:[2,3,0,1] row_mask:0xf bank_mask:0xf bound_ctrl:1
	v_add_f32_dpp v47, v47, v47 quad_perm:[2,3,0,1] row_mask:0xf bank_mask:0xf bound_ctrl:1
	ds_read_b128 v[80:83], v21 offset:19328
	v_add_f32_dpp v46, v46, v46 row_half_mirror row_mask:0xf bank_mask:0xf bound_ctrl:1
	v_add_f32_dpp v47, v47, v47 row_half_mirror row_mask:0xf bank_mask:0xf bound_ctrl:1
	v_pk_mul_f32 v[252:253], v[38:39], v[44:45] op_sel_hi:[0,1]
	v_add_f32_dpp v46, v46, v46 row_mirror row_mask:0xf bank_mask:0xf bound_ctrl:1
	v_add_f32_dpp v47, v47, v47 row_mirror row_mask:0xf bank_mask:0xf bound_ctrl:1
	v_pk_mul_f32 v[254:255], v[38:39], v[44:45] op_sel:[1,0]
	ds_read_b128 v[36:39], v21 offset:20480
	s_waitcnt lgkmcnt(9)
	v_pk_fma_f32 v[248:249], v[12:13], v[24:25], v[248:249] op_sel_hi:[1,0,1]
	v_add_u32_e32 v23, 0x5200, v22
	ds_read2_b32 v[44:45], v23 offset1:4
	v_pk_fma_f32 v[250:251], v[14:15], v[24:25], v[250:251] op_sel:[0,1,0]
	v_pk_fma_f32 v[252:253], v[16:17], v[26:27], v[252:253] op_sel_hi:[1,0,1]
	v_pk_fma_f32 v[254:255], v[18:19], v[26:27], v[254:255] op_sel:[0,1,0]
	ds_read_b128 v[24:27], v21 offset:19712
	v_pk_fma_f32 v[12:13], v[32:33], v[46:47], v[248:249] op_sel_hi:[0,1,1]
	v_pk_fma_f32 v[14:15], v[32:33], v[46:47], v[250:251] op_sel:[1,0,0]
	v_pk_fma_f32 v[16:17], v[34:35], v[46:47], v[252:253] op_sel_hi:[0,1,1]
	v_pk_fma_f32 v[18:19], v[34:35], v[46:47], v[254:255] op_sel:[1,0,0]
	ds_read_b128 v[32:35], v21 offset:20224
	s_waitcnt lgkmcnt(9)
; template <int CTRL> __device__ __forceinline__ float dppf(float x) { return __builtin_bit_cast(float, __builtin_amdgcn_update_dpp(0, __builtin_bit_cast(int, x), CTRL, 0xf, 0xf, true)); }
; __device__ __forceinline__ void scan_item(LAS unsigned char* lds, const ScanPtrs& P, bf16* YC, int item, unsigned* half_cnt, unsigned half_expect) {
;     ...
;             for (int s = 0; s < SC_TC; ++s) {
;                 if (s + 1 < SC_TC) SC_RD(s + 1, nw, nm, nwr, nk, nr, nva, nvb);
;                 __builtin_amdgcn_sched_barrier(0);
;                 const f32x2 m01 = {cm[0], cm[1]}, m23 = {cm[2], cm[3]}, w01 = {cw[0], cw[1]}, w23 = {cw[2], cw[3]}, wr01 = {cwr[0], cwr[1]}, wr23 = {cwr[2], cwr[3]},
;                             k01 = {ck[0], ck[1]}, k23 = {ck[2], ck[3]}, r01 = {cr[0], cr[1]}, r23 = {cr[2], cr[3]};
;                 f32x2 qa = A01 * m01; qa = __builtin_elementwise_fma(A23, m23, qa);
;                 f32x2 qb = B01 * m01; qb = __builtin_elementwise_fma(B23, m23, qb);
;                 float da = qa[0] + qa[1], db = qb[0] + qb[1];
;                 const f32x2 vka01 = k01 * cva, vka23 = k23 * cva, vkb01 = k01 * cvb, vkb23 = k23 * cvb;
;                 da += dppf<0xB1>(da);  db += dppf<0xB1>(db);
;                 da += dppf<0x4E>(da);  db += dppf<0x4E>(db);
;                 da += dppf<0x141>(da); db += dppf<0x141>(db);
;                 da += dppf<0x140>(da); db += dppf<0x140>(db);
;                 const f32x2 sa2 = {da, da}, sb2 = {db, db};
;                 A01 = __builtin_elementwise_fma(A01, w01, __builtin_elementwise_fma(wr01, sa2, vka01)); A23 = __builtin_elementwise_fma(A23, w23, __builtin_elementwise_fma(wr23, sa2, vka23));
;                 B01 = __builtin_elementwise_fma(B01, w01, __builtin_elementwise_fma(wr01, sb2, vkb01)); B23 = __builtin_elementwise_fma(B23, w23, __builtin_elementwise_fma(wr23, sb2, vkb23));
;                 f32x2 ya = A01 * r01; ya = __builtin_elementwise_fma(A23, r23, ya);
;                 f32x2 yb = B01 * r01; yb = __builtin_elementwise_fma(B23, r23, yb);
;                 Y[s * 512] = ya[0] + ya[1]; Y[s * 512 + 64] = yb[0] + yb[1];
;                 __builtin_amdgcn_sched_barrier(0);
;                 cw = nw; cm = nm; cwr = nwr; ck = nk; cr = nr; cva = nva; cvb = nvb;
;             }
	v_pk_mul_f32 v[46:47], v[12:13], v[68:69] op_sel_hi:[1,0]
	v_pk_mul_f32 v[48:49], v[12:13], v[40:41] op_sel_hi:[1,0]
	v_pk_fma_f32 v[46:47], v[14:15], v[68:69], v[46:47] op_sel:[0,1,0]
	v_pk_fma_f32 v[48:49], v[14:15], v[40:41], v[48:49] op_sel:[0,1,0]
	v_pk_fma_f32 v[46:47], v[16:17], v[70:71], v[46:47] op_sel_hi:[1,0,1]
	v_pk_fma_f32 v[48:49], v[16:17], v[42:43], v[48:49] op_sel_hi:[1,0,1]
	v_pk_fma_f32 v[46:47], v[18:19], v[70:71], v[46:47] op_sel:[0,1,0]
	v_pk_fma_f32 v[48:49], v[18:19], v[42:43], v[48:49] op_sel:[0,1,0]
	ds_read_b128 v[68:71], v21 offset:21376
	v_pk_mul_f32 v[248:249], v[76:77], v[84:85] op_sel_hi:[0,1]
	v_pk_mul_f32 v[250:251], v[76:77], v[84:85] op_sel:[1,0]
	v_add_f32_dpp v46, v46, v46 quad_perm:[1,0,3,2] row_mask:0xf bank_mask:0xf bound_ctrl:1
	v_add_f32_dpp v47, v47, v47 quad_perm:[1,0,3,2] row_mask:0xf bank_mask:0xf bound_ctrl:1
	ds_write2st64_b32 v20, v48, v49 offset0:96 offset1:97
	v_add_f32_dpp v46, v46, v46 quad_perm:[2,3,0,1] row_mask:0xf bank_mask:0xf bound_ctrl:1
	v_add_f32_dpp v47, v47, v47 quad_perm:[2,3,0,1] row_mask:0xf bank_mask:0xf bound_ctrl:1
	ds_read_b128 v[40:43], v21 offset:20736
	v_add_f32_dpp v46, v46, v46 row_half_mirror row_mask:0xf bank_mask:0xf bound_ctrl:1
	v_add_f32_dpp v47, v47, v47 row_half_mirror row_mask:0xf bank_mask:0xf bound_ctrl:1
	v_pk_mul_f32 v[252:253], v[78:79], v[84:85] op_sel_hi:[0,1]
	v_add_f32_dpp v46, v46, v46 row_mirror row_mask:0xf bank_mask:0xf bound_ctrl:1
	v_add_f32_dpp v47, v47, v47 row_mirror row_mask:0xf bank_mask:0xf bound_ctrl:1
	v_pk_mul_f32 v[254:255], v[78:79], v[84:85] op_sel:[1,0]
	ds_read_b128 v[76:79], v21 offset:21888
	s_waitcnt lgkmcnt(9)
	v_pk_fma_f32 v[248:249], v[12:13], v[64:65], v[248:249] op_sel_hi:[1,0,1]
	v_add_u32_e32 v23, 0x5780, v22
	ds_read2_b32 v[84:85], v23 offset1:4
	v_pk_fma_f32 v[250:251], v[14:15], v[64:65], v[250:251] op_sel:[0,1,0]
	v_pk_fma_f32 v[252:253], v[16:17], v[66:67], v[252:253] op_sel_hi:[1,0,1]
	v_pk_fma_f32 v[254:255], v[18:19], v[66:67], v[254:255] op_sel:[0,1,0]
	ds_read_b128 v[64:67], v21 offset:21120
	v_pk_fma_f32 v[12:13], v[72:73], v[46:47], v[248:249] op_sel_hi:[0,1,1]
	v_pk_fma_f32 v[14:15], v[72:73], v[46:47], v[250:251] op_sel:[1,0,0]
	v_pk_fma_f32 v[16:17], v[74:75], v[46:47], v[252:253] op_sel_hi:[0,1,1]
	v_pk_fma_f32 v[18:19], v[74:75], v[46:47], v[254:255] op_sel:[1,0,0]
	ds_read_b128 v[72:75], v21 offset:21632
	s_waitcnt lgkmcnt(9)
	v_pk_mul_f32 v[46:47], v[12:13], v[28:29] op_sel_hi:[1,0]
	v_pk_mul_f32 v[48:49], v[12:13], v[80:81] op_sel_hi:[1,0]
	v_pk_fma_f32 v[46:47], v[14:15], v[28:29], v[46:47] op_sel:[0,1,0]
	v_pk_fma_f32 v[48:49], v[14:15], v[80:81], v[48:49] op_sel:[0,1,0]
	v_pk_fma_f32 v[46:47], v[16:17], v[30:31], v[46:47] op_sel_hi:[1,0,1]
	v_pk_fma_f32 v[48:49], v[16:17], v[82:83], v[48:49] op_sel_hi:[1,0,1]
	v_pk_fma_f32 v[46:47], v[18:19], v[30:31], v[46:47] op_sel:[0,1,0]
	v_pk_fma_f32 v[48:49], v[18:19], v[82:83], v[48:49] op_sel:[0,1,0]
	v_pk_mul_f32 v[248:249], v[36:37], v[44:45] op_sel_hi:[0,1]
	v_pk_mul_f32 v[250:251], v[36:37], v[44:45] op_sel:[1,0]
	v_add_f32_dpp v46, v46, v46 quad_perm:[1,0,3,2] row_mask:0xf bank_mask:0xf bound_ctrl:1
	v_add_f32_dpp v47, v47, v47 quad_perm:[1,0,3,2] row_mask:0xf bank_mask:0xf bound_ctrl:1
	ds_write2st64_b32 v20, v48, v49 offset0:104 offset1:105
	v_add_f32_dpp v46, v46, v46 quad_perm:[2,3,0,1] row_mask:0xf bank_mask:0xf bound_ctrl:1
	v_add_f32_dpp v47, v47, v47 quad_perm:[2,3,0,1] row_mask:0xf bank_mask:0xf bound_ctrl:1
	ds_read_b128 v[80:83], v21 offset:22144
	v_add_f32_dpp v46, v46, v46 row_half_mirror row_mask:0xf bank_mask:0xf bound_ctrl:1
	v_add_f32_dpp v47, v47, v47 row_half_mirror row_mask:0xf bank_mask:0xf bound_ctrl:1
	v_pk_mul_f32 v[252:253], v[38:39], v[44:45] op_sel_hi:[0,1]
	v_add_f32_dpp v46, v46, v46 row_mirror row_mask:0xf bank_mask:0xf bound_ctrl:1
	v_add_f32_dpp v47, v47, v47 row_mirror row_mask:0xf bank_mask:0xf bound_ctrl:1
	v_pk_mul_f32 v[254:255], v[38:39], v[44:45] op_sel:[1,0]
	s_waitcnt lgkmcnt(9)
; template <int CTRL> __device__ __forceinline__ float dppf(float x) { return __builtin_bit_cast(float, __builtin_amdgcn_update_dpp(0, __builtin_bit_cast(int, x), CTRL, 0xf, 0xf, true)); }
; __device__ __forceinline__ void scan_item(LAS unsigned char* lds, const ScanPtrs& P, bf16* YC, int item, unsigned* half_cnt, unsigned half_expect) {
;     ...
;             for (int s = 0; s < SC_TC; ++s) {
;                 if (s + 1 < SC_TC) SC_RD(s + 1, nw, nm, nwr, nk, nr, nva, nvb);
;                 __builtin_amdgcn_sched_barrier(0);
;                 const f32x2 m01 = {cm[0], cm[1]}, m23 = {cm[2], cm[3]}, w01 = {cw[0], cw[1]}, w23 = {cw[2], cw[3]}, wr01 = {cwr[0], cwr[1]}, wr23 = {cwr[2], cwr[3]},
;                             k01 = {ck[0], ck[1]}, k23 = {ck[2], ck[3]}, r01 = {cr[0], cr[1]}, r23 = {cr[2], cr[3]};
;                 f32x2 qa = A01 * m01; qa = __builtin_elementwise_fma(A23, m23, qa);
;                 f32x2 qb = B01 * m01; qb = __builtin_elementwise_fma(B23, m23, qb);
;                 float da = qa[0] + qa[1], db = qb[0] + qb[1];
;                 const f32x2 vka01 = k01 * cva, vka23 = k23 * cva, vkb01 = k01 * cvb, vkb23 = k23 * cvb;
;                 da += dppf<0xB1>(da);  db += dppf<0xB1>(db);
;                 da += dppf<0x4E>(da);  db += dppf<0x4E>(db);
;                 da += dppf<0x141>(da); db += dppf<0x141>(db);
;                 da += dppf<0x140>(da); db += dppf<0x140>(db);
;                 const f32x2 sa2 = {da, da}, sb2 = {db, db};
;                 A01 = __builtin_elementwise_fma(A01, w01, __builtin_elementwise_fma(wr01, sa2, vka01)); A23 = __builtin_elementwise_fma(A23, w23, __builtin_elementwise_fma(wr23, sa2, vka23));
;                 B01 = __builtin_elementwise_fma(B01, w01, __builtin_elementwise_fma(wr01, sb2, vkb01)); B23 = __builtin_elementwise_fma(B23, w23, __builtin_elementwise_fma(wr23, sb2, vkb23));
;                 f32x2 ya = A01 * r01; ya = __builtin_elementwise_fma(A23, r23, ya);
;                 f32x2 yb = B01 * r01; yb = __builtin_elementwise_fma(B23, r23, yb);
;                 Y[s * 512] = ya[0] + ya[1]; Y[s * 512 + 64] = yb[0] + yb[1];
;                 __builtin_amdgcn_sched_barrier(0);
;                 cw = nw; cm = nm; cwr = nwr; ck = nk; cr = nr; cva = nva; cvb = nvb;
;             }
;     ...
;             __syncthreads();
;         }
	v_pk_fma_f32 v[248:249], v[12:13], v[24:25], v[248:249] op_sel_hi:[1,0,1]
	v_pk_fma_f32 v[250:251], v[14:15], v[24:25], v[250:251] op_sel:[0,1,0]
	v_pk_fma_f32 v[252:253], v[16:17], v[26:27], v[252:253] op_sel_hi:[1,0,1]
	v_pk_fma_f32 v[254:255], v[18:19], v[26:27], v[254:255] op_sel:[0,1,0]
	v_pk_fma_f32 v[12:13], v[32:33], v[46:47], v[248:249] op_sel_hi:[0,1,1]
	v_pk_fma_f32 v[14:15], v[32:33], v[46:47], v[250:251] op_sel:[1,0,0]
	v_pk_fma_f32 v[16:17], v[34:35], v[46:47], v[252:253] op_sel_hi:[0,1,1]
	v_pk_fma_f32 v[18:19], v[34:35], v[46:47], v[254:255] op_sel:[1,0,0]
	s_waitcnt lgkmcnt(4)
	v_pk_mul_f32 v[46:47], v[12:13], v[68:69] op_sel_hi:[1,0]
	v_pk_mul_f32 v[48:49], v[12:13], v[40:41] op_sel_hi:[1,0]
	v_pk_fma_f32 v[46:47], v[14:15], v[68:69], v[46:47] op_sel:[0,1,0]
	v_pk_fma_f32 v[48:49], v[14:15], v[40:41], v[48:49] op_sel:[0,1,0]
	v_pk_fma_f32 v[46:47], v[16:17], v[70:71], v[46:47] op_sel_hi:[1,0,1]
	v_pk_fma_f32 v[48:49], v[16:17], v[42:43], v[48:49] op_sel_hi:[1,0,1]
	v_pk_fma_f32 v[46:47], v[18:19], v[70:71], v[46:47] op_sel:[0,1,0]
	v_pk_fma_f32 v[48:49], v[18:19], v[42:43], v[48:49] op_sel:[0,1,0]
	v_pk_mul_f32 v[248:249], v[76:77], v[84:85] op_sel_hi:[0,1]
	v_pk_mul_f32 v[250:251], v[76:77], v[84:85] op_sel:[1,0]
	v_add_f32_dpp v46, v46, v46 quad_perm:[1,0,3,2] row_mask:0xf bank_mask:0xf bound_ctrl:1
	v_add_f32_dpp v47, v47, v47 quad_perm:[1,0,3,2] row_mask:0xf bank_mask:0xf bound_ctrl:1
	ds_write2st64_b32 v20, v48, v49 offset0:112 offset1:113
	v_add_f32_dpp v46, v46, v46 quad_perm:[2,3,0,1] row_mask:0xf bank_mask:0xf bound_ctrl:1
	v_add_f32_dpp v47, v47, v47 quad_perm:[2,3,0,1] row_mask:0xf bank_mask:0xf bound_ctrl:1
	v_pk_mul_f32 v[252:253], v[78:79], v[84:85] op_sel_hi:[0,1]
	v_add_f32_dpp v46, v46, v46 row_half_mirror row_mask:0xf bank_mask:0xf bound_ctrl:1
	v_add_f32_dpp v47, v47, v47 row_half_mirror row_mask:0xf bank_mask:0xf bound_ctrl:1
	v_pk_mul_f32 v[254:255], v[78:79], v[84:85] op_sel:[1,0]
	v_add_f32_dpp v46, v46, v46 row_mirror row_mask:0xf bank_mask:0xf bound_ctrl:1
	v_add_f32_dpp v47, v47, v47 row_mirror row_mask:0xf bank_mask:0xf bound_ctrl:1
	s_waitcnt lgkmcnt(3)
	v_pk_fma_f32 v[248:249], v[12:13], v[64:65], v[248:249] op_sel_hi:[1,0,1]
	v_pk_fma_f32 v[250:251], v[14:15], v[64:65], v[250:251] op_sel:[0,1,0]
	v_pk_fma_f32 v[252:253], v[16:17], v[66:67], v[252:253] op_sel_hi:[1,0,1]
	v_pk_fma_f32 v[254:255], v[18:19], v[66:67], v[254:255] op_sel:[0,1,0]
	v_pk_fma_f32 v[12:13], v[72:73], v[46:47], v[248:249] op_sel_hi:[0,1,1]
	v_pk_fma_f32 v[14:15], v[72:73], v[46:47], v[250:251] op_sel:[1,0,0]
	v_pk_fma_f32 v[16:17], v[74:75], v[46:47], v[252:253] op_sel_hi:[0,1,1]
	v_pk_fma_f32 v[18:19], v[74:75], v[46:47], v[254:255] op_sel:[1,0,0]
	s_waitcnt lgkmcnt(1)
	s_add_i32 s0, s0, 1
	v_pk_mul_f32 v[48:49], v[12:13], v[80:81] op_sel_hi:[1,0]
	s_and_b32 s2, s0, 1
	v_pk_fma_f32 v[48:49], v[14:15], v[80:81], v[48:49] op_sel:[0,1,0]
	s_mul_i32 s3, s2, 0x5800
	v_pk_fma_f32 v[48:49], v[16:17], v[82:83], v[48:49] op_sel_hi:[1,0,1]
	s_addk_i32 s3, 0x100
	v_pk_fma_f32 v[48:49], v[18:19], v[82:83], v[48:49] op_sel:[0,1,0]
	v_lshl_add_u32 v22, v6, 2, s3
	v_add_u32_e32 v21, s3, v3
	ds_write2st64_b32 v20, v48, v49 offset0:120 offset1:121
	v_lshl_add_u32 v23, s2, 15, v11
	v_add_u32_e32 v20, 0xb000, v23
	s_cmpk_eq_i32 s0, 0x100
	s_waitcnt lgkmcnt(0)
	s_barrier
	s_cbranch_scc0 .LBB0_728
	s_setprio 0
	s_mov_b64 s[2:3], 0
